# diff-attn k-loop: rotated MFMA/softmax phases, 4-slot LDS fragment ring, half-offset waves, s_setprio 1 over the MFMA phase
# speedup vs baseline: 1.0357x; 1.0125x over previous
.Ldtop_skip:
	v_lshl_add_u32 v196, s11, 13, v211
	s_add_i32 s0, s40, 0xffff8000
	s_and_b32 s0, s0, 0x8000
	v_add_u32_e32 v221, s0, v216
	v_add_u32_e32 v162, v196, v212
	v_add_u32_e32 v163, v196, v213
	v_add_u32_e32 v164, v196, v214
	v_add_u32_e32 v165, v196, v215
	v_add_u32_e32 v166, v221, v217
	v_add_u32_e32 v167, v221, v218
	v_add_u32_e32 v168, v221, v219
	v_add_u32_e32 v169, v221, v220
	ds_read_b128 v[130:133], v162
	ds_read_b128 v[134:137], v162 offset:4096
	ds_read_b128 v[138:141], v163
	ds_read_b128 v[142:145], v163 offset:4096
	s_setprio 1
	s_waitcnt lgkmcnt(3)
	v_mfma_f32_32x32x16_bf16 v[98:113], v[130:133], v[146:149], v[66:81]
	ds_read_b128 v[130:133], v164
	s_waitcnt lgkmcnt(3)
	v_mfma_f32_32x32x16_bf16 v[82:97], v[134:137], v[146:149], v[66:81]
	ds_read_b128 v[134:137], v164 offset:4096
	s_waitcnt lgkmcnt(3)
	v_mfma_f32_32x32x16_bf16 v[98:113], v[138:141], v[150:153], v[98:113]
	ds_read_b128 v[138:141], v165
	s_waitcnt lgkmcnt(3)
	v_mfma_f32_32x32x16_bf16 v[82:97], v[142:145], v[150:153], v[82:97]
	ds_read_b128 v[142:145], v165 offset:4096
	s_waitcnt lgkmcnt(3)
	v_mfma_f32_32x32x16_bf16 v[98:113], v[130:133], v[154:157], v[98:113]
	ds_read_b128 v[130:133], v166 offset:32768
	s_waitcnt lgkmcnt(3)
	v_mfma_f32_32x32x16_bf16 v[82:97], v[134:137], v[154:157], v[82:97]
	ds_read_b128 v[134:137], v166 offset:36864
	s_waitcnt lgkmcnt(3)
	v_mfma_f32_32x32x16_bf16 v[98:113], v[138:141], v[158:161], v[98:113]
	ds_read_b128 v[138:141], v166 offset:40960
	s_waitcnt lgkmcnt(3)
	v_mfma_f32_32x32x16_bf16 v[82:97], v[142:145], v[158:161], v[82:97]
	ds_read_b128 v[142:145], v166 offset:45056
	s_waitcnt lgkmcnt(3)
	v_mfma_f32_32x32x16_bf16 v[2:17], v[130:133], v[114:117], v[2:17]
	ds_read_b128 v[130:133], v167 offset:32768
	s_waitcnt lgkmcnt(3)
	v_mfma_f32_32x32x16_bf16 v[50:65], v[134:137], v[114:117], v[50:65]
	ds_read_b128 v[134:137], v167 offset:36864
	s_waitcnt lgkmcnt(3)
	v_mfma_f32_32x32x16_bf16 v[34:49], v[138:141], v[114:117], v[34:49]
	ds_read_b128 v[138:141], v167 offset:40960
	s_waitcnt lgkmcnt(3)
	v_mfma_f32_32x32x16_bf16 v[18:33], v[142:145], v[114:117], v[18:33]
	ds_read_b128 v[142:145], v167 offset:45056
	s_waitcnt lgkmcnt(3)
	v_mfma_f32_32x32x16_bf16 v[2:17], v[130:133], v[118:121], v[2:17]
	ds_read_b128 v[130:133], v168 offset:32768
	s_waitcnt lgkmcnt(3)
	v_mfma_f32_32x32x16_bf16 v[50:65], v[134:137], v[118:121], v[50:65]
	ds_read_b128 v[134:137], v168 offset:36864
	s_waitcnt lgkmcnt(3)
	v_mfma_f32_32x32x16_bf16 v[34:49], v[138:141], v[118:121], v[34:49]
	ds_read_b128 v[138:141], v168 offset:40960
	s_waitcnt lgkmcnt(3)
	v_mfma_f32_32x32x16_bf16 v[18:33], v[142:145], v[118:121], v[18:33]
	ds_read_b128 v[142:145], v168 offset:45056
	s_waitcnt lgkmcnt(3)
	v_mfma_f32_32x32x16_bf16 v[2:17], v[130:133], v[122:125], v[2:17]
	ds_read_b128 v[130:133], v169 offset:32768
	s_waitcnt lgkmcnt(3)
	v_mfma_f32_32x32x16_bf16 v[50:65], v[134:137], v[122:125], v[50:65]
	ds_read_b128 v[134:137], v169 offset:36864
	s_waitcnt lgkmcnt(3)
	v_mfma_f32_32x32x16_bf16 v[34:49], v[138:141], v[122:125], v[34:49]
	ds_read_b128 v[138:141], v169 offset:40960
	s_waitcnt lgkmcnt(3)
	v_mfma_f32_32x32x16_bf16 v[18:33], v[142:145], v[122:125], v[18:33]
	ds_read_b128 v[142:145], v169 offset:45056
	s_waitcnt lgkmcnt(3)
	v_mfma_f32_32x32x16_bf16 v[2:17], v[130:133], v[126:129], v[2:17]
	s_waitcnt lgkmcnt(2)
	v_mfma_f32_32x32x16_bf16 v[50:65], v[134:137], v[126:129], v[50:65]
	s_waitcnt lgkmcnt(1)
	v_mfma_f32_32x32x16_bf16 v[34:49], v[138:141], v[126:129], v[34:49]
	s_waitcnt lgkmcnt(0)
	v_mfma_f32_32x32x16_bf16 v[18:33], v[142:145], v[126:129], v[18:33]
	s_setprio 0
	s_mov_b64 s[6:7], 0
	s_mov_b64 s[8:9], 0

.Ldv_skip2:
	s_and_b32 s0, s5, 0x4000
	v_add_u32_e32 v196, s0, v211
	v_lshl_add_u32 v221, s11, 14, v216
	v_add_u32_e32 v162, v196, v212
	v_add_u32_e32 v163, v196, v213
	v_add_u32_e32 v164, v196, v214
	v_add_u32_e32 v165, v196, v215
	v_add_u32_e32 v166, v221, v217
	v_add_u32_e32 v167, v221, v218
	v_add_u32_e32 v168, v221, v219
	v_add_u32_e32 v169, v221, v220
	ds_read_b128 v[130:133], v162
	ds_read_b128 v[134:137], v162 offset:4096
	ds_read_b128 v[138:141], v163
	ds_read_b128 v[142:145], v163 offset:4096
	s_setprio 1
	s_waitcnt lgkmcnt(3)
	v_mfma_f32_32x32x16_bf16 v[98:113], v[130:133], v[146:149], v[66:81]
	ds_read_b128 v[130:133], v164
	s_waitcnt lgkmcnt(3)
	v_mfma_f32_32x32x16_bf16 v[82:97], v[134:137], v[146:149], v[66:81]
	ds_read_b128 v[134:137], v164 offset:4096
	s_waitcnt lgkmcnt(3)
	v_mfma_f32_32x32x16_bf16 v[98:113], v[138:141], v[150:153], v[98:113]
	ds_read_b128 v[138:141], v165
	s_waitcnt lgkmcnt(3)
	v_mfma_f32_32x32x16_bf16 v[82:97], v[142:145], v[150:153], v[82:97]
	ds_read_b128 v[142:145], v165 offset:4096
	s_waitcnt lgkmcnt(3)
	v_mfma_f32_32x32x16_bf16 v[98:113], v[130:133], v[154:157], v[98:113]
	ds_read_b128 v[130:133], v166 offset:32768
	s_waitcnt lgkmcnt(3)
	v_mfma_f32_32x32x16_bf16 v[82:97], v[134:137], v[154:157], v[82:97]
	ds_read_b128 v[134:137], v166 offset:36864
	s_waitcnt lgkmcnt(3)
	v_mfma_f32_32x32x16_bf16 v[98:113], v[138:141], v[158:161], v[98:113]
	ds_read_b128 v[138:141], v166 offset:40960
	s_waitcnt lgkmcnt(3)
	v_mfma_f32_32x32x16_bf16 v[82:97], v[142:145], v[158:161], v[82:97]
	ds_read_b128 v[142:145], v166 offset:45056
	s_waitcnt lgkmcnt(3)
	v_mfma_f32_32x32x16_bf16 v[2:17], v[130:133], v[114:117], v[2:17]
	ds_read_b128 v[130:133], v167 offset:32768
	s_waitcnt lgkmcnt(3)
	v_mfma_f32_32x32x16_bf16 v[50:65], v[134:137], v[114:117], v[50:65]
	ds_read_b128 v[134:137], v167 offset:36864
	s_waitcnt lgkmcnt(3)
	v_mfma_f32_32x32x16_bf16 v[34:49], v[138:141], v[114:117], v[34:49]
	ds_read_b128 v[138:141], v167 offset:40960
	s_waitcnt lgkmcnt(3)
	v_mfma_f32_32x32x16_bf16 v[18:33], v[142:145], v[114:117], v[18:33]
	ds_read_b128 v[142:145], v167 offset:45056
	s_waitcnt lgkmcnt(3)
	v_mfma_f32_32x32x16_bf16 v[2:17], v[130:133], v[118:121], v[2:17]
	ds_read_b128 v[130:133], v168 offset:32768
	s_waitcnt lgkmcnt(3)
	v_mfma_f32_32x32x16_bf16 v[50:65], v[134:137], v[118:121], v[50:65]
	ds_read_b128 v[134:137], v168 offset:36864
	s_waitcnt lgkmcnt(3)
	v_mfma_f32_32x32x16_bf16 v[34:49], v[138:141], v[118:121], v[34:49]
	ds_read_b128 v[138:141], v168 offset:40960
	s_waitcnt lgkmcnt(3)
	v_mfma_f32_32x32x16_bf16 v[18:33], v[142:145], v[118:121], v[18:33]
	ds_read_b128 v[142:145], v168 offset:45056
	s_waitcnt lgkmcnt(3)
	v_mfma_f32_32x32x16_bf16 v[2:17], v[130:133], v[122:125], v[2:17]
	ds_read_b128 v[130:133], v169 offset:32768
	s_waitcnt lgkmcnt(3)
	v_mfma_f32_32x32x16_bf16 v[50:65], v[134:137], v[122:125], v[50:65]
	ds_read_b128 v[134:137], v169 offset:36864
	s_waitcnt lgkmcnt(3)
	v_mfma_f32_32x32x16_bf16 v[34:49], v[138:141], v[122:125], v[34:49]
	ds_read_b128 v[138:141], v169 offset:40960
	s_waitcnt lgkmcnt(3)
	v_mfma_f32_32x32x16_bf16 v[18:33], v[142:145], v[122:125], v[18:33]
	ds_read_b128 v[142:145], v169 offset:45056
	s_waitcnt lgkmcnt(3)
	v_mfma_f32_32x32x16_bf16 v[2:17], v[130:133], v[126:129], v[2:17]
	s_waitcnt lgkmcnt(2)
	v_mfma_f32_32x32x16_bf16 v[50:65], v[134:137], v[126:129], v[50:65]
	s_waitcnt lgkmcnt(1)
	v_mfma_f32_32x32x16_bf16 v[34:49], v[138:141], v[126:129], v[34:49]
	s_waitcnt lgkmcnt(0)
	v_mfma_f32_32x32x16_bf16 v[18:33], v[142:145], v[126:129], v[18:33]
	s_setprio 0
	s_cmp_ge_u32 s41, s30
	s_cbranch_scc1 .Ldend_skip
	v_readlane_b32 s0, v252, 7
	s_cmpk_lt_u32 s0, 0x100
	s_cbranch_scc0 .Ldend_skip
	s_mov_b64 s[6:7], 0
	s_mov_b64 s[8:9], 0
